# attention loops: cross-half max exchange via v_permlane32_swap instead of ds_bpermute+wait; GLA 2a softplus interleaved with next position fmacs
# speedup vs baseline: 1.0112x; 1.0012x over previous
.LBB0_348:
	s_and_b32 s10, s21, 1
	s_mul_i32 s11, s10, 0x2400
	v_add_u32_e32 v0, s11, v128
	ds_read_b128 v[2:5], v0
	ds_read_b128 v[6:9], v0 offset:32
	s_waitcnt lgkmcnt(1)
	v_mfma_f32_32x32x16_bf16 v[64:79], v[2:5], v[92:95], 0
	s_waitcnt lgkmcnt(0)
	v_mfma_f32_32x32x16_bf16 v[64:79], v[6:9], v[88:91], v[64:79]
	ds_read_b128 v[2:5], v0 offset:64
	ds_read_b128 v[6:9], v0 offset:96
	s_waitcnt lgkmcnt(1)
	v_mfma_f32_32x32x16_bf16 v[64:79], v[2:5], v[84:87], v[64:79]
	ds_read_b128 v[2:5], v0 offset:4608
	ds_read_b128 v[10:13], v0 offset:4640
	s_waitcnt lgkmcnt(1)
	v_mfma_f32_32x32x16_bf16 v[48:63], v[2:5], v[92:95], 0
	s_waitcnt lgkmcnt(0)
	v_mfma_f32_32x32x16_bf16 v[48:63], v[10:13], v[88:91], v[48:63]
	ds_read_b128 v[2:5], v0 offset:4672
	ds_read_b128 v[10:13], v0 offset:4704
	s_waitcnt lgkmcnt(1)
	v_mfma_f32_32x32x16_bf16 v[48:63], v[2:5], v[84:87], v[48:63]
	s_waitcnt lgkmcnt(0)
	v_mfma_f32_32x32x16_bf16 v[48:63], v[10:13], v[80:83], v[48:63]
	v_mfma_f32_32x32x16_bf16 v[64:79], v[6:9], v[80:83], v[64:79]
	s_nop 10
	v_max_f32_e32 v0, v48, v48
	v_max_f32_e32 v2, v64, v64
	v_max_f32_e32 v0, v2, v0
	v_max3_f32 v0, v0, v65, v49
	v_max3_f32 v0, v0, v66, v50
	v_max3_f32 v0, v0, v67, v51
	v_max3_f32 v0, v0, v68, v52
	v_max3_f32 v0, v0, v69, v53
	v_max3_f32 v0, v0, v70, v54
	v_max3_f32 v0, v0, v71, v55
	v_max3_f32 v0, v0, v72, v56
	v_max3_f32 v0, v0, v73, v57
	v_max3_f32 v0, v0, v74, v58
	v_max3_f32 v0, v0, v75, v59
	v_max3_f32 v0, v0, v76, v60
	v_max3_f32 v0, v0, v77, v61
	v_max3_f32 v0, v0, v78, v62
	v_max3_f32 v0, v0, v79, v63
	v_mov_b32_e32 v2, v0
	s_nop 1
	v_permlane32_swap_b32_e32 v0, v2
	s_nop 0
	v_max_f32_e32 v0, v0, v2
	v_mul_f32_e32 v0, 0x3e38aa3b, v0
	v_add_f32_e32 v2, 0x41000000, v120
	v_cmp_gt_f32_e32 vcc, v0, v2
	s_cbranch_vccz .LBB0_359
	v_max_f32_e32 v0, v0, v0
	v_max_f32_e32 v2, v120, v120
	v_max_f32_e32 v2, v2, v0
	v_sub_f32_e32 v0, v120, v2
	v_exp_f32_e32 v0, v0
	v_mov_b32_e32 v120, v2
	v_pk_mul_f32 v[46:47], v[46:47], v[0:1] op_sel_hi:[1,0]
	v_pk_mul_f32 v[44:45], v[44:45], v[0:1] op_sel_hi:[1,0]
	v_pk_mul_f32 v[42:43], v[42:43], v[0:1] op_sel_hi:[1,0]
	v_pk_mul_f32 v[40:41], v[40:41], v[0:1] op_sel_hi:[1,0]
	v_pk_mul_f32 v[38:39], v[38:39], v[0:1] op_sel_hi:[1,0]
	v_pk_mul_f32 v[36:37], v[36:37], v[0:1] op_sel_hi:[1,0]
	v_pk_mul_f32 v[34:35], v[34:35], v[0:1] op_sel_hi:[1,0]
	v_pk_mul_f32 v[32:33], v[32:33], v[0:1] op_sel_hi:[1,0]
	v_pk_mul_f32 v[30:31], v[30:31], v[0:1] op_sel_hi:[1,0]
	v_pk_mul_f32 v[28:29], v[28:29], v[0:1] op_sel_hi:[1,0]
	v_pk_mul_f32 v[26:27], v[26:27], v[0:1] op_sel_hi:[1,0]
	v_pk_mul_f32 v[24:25], v[24:25], v[0:1] op_sel_hi:[1,0]
	v_pk_mul_f32 v[22:23], v[22:23], v[0:1] op_sel_hi:[1,0]
	v_pk_mul_f32 v[20:21], v[20:21], v[0:1] op_sel_hi:[1,0]
	v_pk_mul_f32 v[18:19], v[18:19], v[0:1] op_sel_hi:[1,0]
	v_pk_mul_f32 v[16:17], v[16:17], v[0:1] op_sel_hi:[1,0]
	v_mul_f32_e32 v115, v115, v0

.LBB0_357:
	s_and_b32 s12, s21, 1
	s_mul_i32 s13, s12, 0x2400
	v_add_u32_e32 v0, s13, v128
	ds_read_b128 v[48:51], v0
	ds_read_b128 v[52:55], v0 offset:32
	s_waitcnt lgkmcnt(1)
	v_mfma_f32_32x32x16_bf16 v[64:79], v[48:51], v[92:95], 0
	ds_read_b128 v[48:51], v0 offset:64
	ds_read_b128 v[132:135], v0 offset:96
	s_waitcnt lgkmcnt(2)
	v_mfma_f32_32x32x16_bf16 v[64:79], v[52:55], v[88:91], v[64:79]
	s_waitcnt lgkmcnt(1)
	v_mfma_f32_32x32x16_bf16 v[64:79], v[48:51], v[84:87], v[64:79]
	ds_read_b128 v[48:51], v0 offset:4608
	ds_read_b128 v[136:139], v0 offset:4640
	s_waitcnt lgkmcnt(1)
	v_mfma_f32_32x32x16_bf16 v[48:63], v[48:51], v[92:95], 0
	s_waitcnt lgkmcnt(0)
	v_mfma_f32_32x32x16_bf16 v[48:63], v[136:139], v[88:91], v[48:63]
	ds_read_b128 v[136:139], v0 offset:4672
	ds_read_b128 v[140:143], v0 offset:4704
	s_waitcnt lgkmcnt(1)
	v_mfma_f32_32x32x16_bf16 v[48:63], v[136:139], v[84:87], v[48:63]
	s_waitcnt lgkmcnt(0)
	v_mfma_f32_32x32x16_bf16 v[48:63], v[140:143], v[80:83], v[48:63]
	v_mfma_f32_32x32x16_bf16 v[64:79], v[132:135], v[80:83], v[64:79]
	v_lshl_add_u64 v[2:3], v[124:125], 0, s[10:11]
	v_add_co_u32_e32 v4, vcc, 0xaa08000, v2
	v_lshl_add_u64 v[14:15], v[122:123], 0, s[10:11]
	s_nop 0
	v_addc_co_u32_e32 v5, vcc, 0, v3, vcc
	v_add_co_u32_e32 v2, vcc, 0xaa0c000, v2
	s_nop 0
	v_addc_co_u32_e32 v3, vcc, 0, v3, vcc
	global_load_dwordx4 v[10:13], v[4:5], off
	global_load_dwordx4 v[96:99], v[2:3], off
	s_nop 0
	global_load_dwordx4 v[2:5], v[14:15], off offset:-512
	global_load_dwordx4 v[6:9], v[14:15], off
	v_max_f32_e32 v0, v48, v48
	v_max_f32_e32 v14, v64, v64
	v_max_f32_e32 v0, v14, v0
	v_max3_f32 v0, v0, v65, v49
	v_max3_f32 v0, v0, v66, v50
	v_max3_f32 v0, v0, v67, v51
	v_max3_f32 v0, v0, v68, v52
	v_max3_f32 v0, v0, v69, v53
	v_max3_f32 v0, v0, v70, v54
	v_max3_f32 v0, v0, v71, v55
	v_max3_f32 v0, v0, v72, v56
	v_max3_f32 v0, v0, v73, v57
	v_max3_f32 v0, v0, v74, v58
	v_max3_f32 v0, v0, v75, v59
	v_max3_f32 v0, v0, v76, v60
	v_max3_f32 v0, v0, v77, v61
	v_max3_f32 v0, v0, v78, v62
	v_max3_f32 v0, v0, v79, v63
	v_mov_b32_e32 v14, v0
	s_nop 1
	v_permlane32_swap_b32_e32 v0, v14
	s_nop 0
	v_max_f32_e32 v0, v0, v14
	v_mul_f32_e32 v0, 0x3e38aa3b, v0
	v_add_f32_e32 v14, 0x41000000, v120
	v_cmp_gt_f32_e32 vcc, v0, v14
	s_cbranch_vccz .LBB0_356
	v_max_f32_e32 v0, v0, v0
	v_max_f32_e32 v14, v120, v120
	v_max_f32_e32 v14, v14, v0
	v_sub_f32_e32 v0, v120, v14
	v_exp_f32_e32 v0, v0
	v_mov_b32_e32 v120, v14
	v_pk_mul_f32 v[46:47], v[46:47], v[0:1] op_sel_hi:[1,0]
	v_pk_mul_f32 v[44:45], v[44:45], v[0:1] op_sel_hi:[1,0]
	v_pk_mul_f32 v[42:43], v[42:43], v[0:1] op_sel_hi:[1,0]
	v_pk_mul_f32 v[40:41], v[40:41], v[0:1] op_sel_hi:[1,0]
	v_pk_mul_f32 v[38:39], v[38:39], v[0:1] op_sel_hi:[1,0]
	v_pk_mul_f32 v[36:37], v[36:37], v[0:1] op_sel_hi:[1,0]
	v_pk_mul_f32 v[34:35], v[34:35], v[0:1] op_sel_hi:[1,0]
	v_pk_mul_f32 v[32:33], v[32:33], v[0:1] op_sel_hi:[1,0]
	v_pk_mul_f32 v[30:31], v[30:31], v[0:1] op_sel_hi:[1,0]
	v_pk_mul_f32 v[28:29], v[28:29], v[0:1] op_sel_hi:[1,0]
	v_pk_mul_f32 v[26:27], v[26:27], v[0:1] op_sel_hi:[1,0]
	v_pk_mul_f32 v[24:25], v[24:25], v[0:1] op_sel_hi:[1,0]
	v_pk_mul_f32 v[22:23], v[22:23], v[0:1] op_sel_hi:[1,0]
	v_pk_mul_f32 v[20:21], v[20:21], v[0:1] op_sel_hi:[1,0]
	v_pk_mul_f32 v[18:19], v[18:19], v[0:1] op_sel_hi:[1,0]
	v_pk_mul_f32 v[16:17], v[16:17], v[0:1] op_sel_hi:[1,0]
	v_mul_f32_e32 v115, v115, v0
	s_branch .LBB0_356

.LBB0_2444:
	s_and_b32 s22, s24, 1
	s_mul_i32 s23, s22, 0x3400
	v_add_u32_e32 v96, s23, v145
	ds_read_b128 v[32:35], v96
	ds_read_b128 v[36:39], v96 offset:32
	s_waitcnt lgkmcnt(1)
	v_mfma_f32_32x32x16_bf16 v[48:63], v[32:35], v[84:87], 0
	s_waitcnt lgkmcnt(0)
	v_mfma_f32_32x32x16_bf16 v[48:63], v[36:39], v[80:83], v[48:63]
	ds_read_b128 v[32:35], v96 offset:64
	ds_read_b128 v[36:39], v96 offset:96
	s_waitcnt lgkmcnt(1)
	v_mfma_f32_32x32x16_bf16 v[48:63], v[32:35], v[76:79], v[48:63]
	ds_read_b128 v[32:35], v96 offset:128
	ds_read_b128 v[88:91], v96 offset:160
	s_waitcnt lgkmcnt(2)
	v_mfma_f32_32x32x16_bf16 v[48:63], v[36:39], v[72:75], v[48:63]
	s_waitcnt lgkmcnt(1)
	v_mfma_f32_32x32x16_bf16 v[48:63], v[32:35], v[68:71], v[48:63]
	ds_read_b128 v[32:35], v96 offset:6656
	ds_read_b128 v[92:95], v96 offset:6688
	s_waitcnt lgkmcnt(1)
	v_mfma_f32_32x32x16_bf16 v[32:47], v[32:35], v[84:87], 0
	s_waitcnt lgkmcnt(0)
	v_mfma_f32_32x32x16_bf16 v[32:47], v[92:95], v[80:83], v[32:47]
	ds_read_b128 v[80:83], v96 offset:6720
	ds_read_b128 v[84:87], v96 offset:6752
	s_waitcnt lgkmcnt(1)
	v_mfma_f32_32x32x16_bf16 v[32:47], v[80:83], v[76:79], v[32:47]
	s_waitcnt lgkmcnt(0)
	v_mfma_f32_32x32x16_bf16 v[32:47], v[84:87], v[72:75], v[32:47]
	ds_read_b128 v[72:75], v96 offset:6784
	ds_read_b128 v[76:79], v96 offset:6816
	s_waitcnt lgkmcnt(1)
	v_mfma_f32_32x32x16_bf16 v[32:47], v[72:75], v[68:71], v[32:47]
	s_waitcnt lgkmcnt(0)
	v_mfma_f32_32x32x16_bf16 v[32:47], v[76:79], v[64:67], v[32:47]
	v_mfma_f32_32x32x16_bf16 v[48:63], v[88:91], v[64:67], v[48:63]
	s_nop 10
	v_max_f32_e32 v68, v32, v32
	v_max_f32_e32 v64, v48, v48
	v_max_f32_e32 v64, v64, v68
	v_max3_f32 v64, v64, v49, v33
	v_max3_f32 v64, v64, v50, v34
	v_max3_f32 v64, v64, v51, v35
	v_max3_f32 v64, v64, v52, v36
	v_max3_f32 v64, v64, v53, v37
	v_max3_f32 v64, v64, v54, v38
	v_max3_f32 v64, v64, v55, v39
	v_max3_f32 v64, v64, v56, v40
	v_max3_f32 v64, v64, v57, v41
	v_max3_f32 v64, v64, v58, v42
	v_max3_f32 v64, v64, v59, v43
	v_max3_f32 v64, v64, v60, v44
	v_max3_f32 v64, v64, v61, v45
	v_max3_f32 v64, v64, v62, v46
	v_max3_f32 v64, v64, v63, v47
	v_mov_b32_e32 v65, v64
	s_nop 1
	v_permlane32_swap_b32_e32 v64, v65
	s_nop 0
	v_max_f32_e32 v64, v64, v65
	v_mul_f32_e32 v64, 0x3e16c740, v64
	v_add_f32_e32 v65, 0x41000000, v138
	v_cmp_gt_f32_e32 vcc, v64, v65
	s_cbranch_vccz .LBB0_2455
	v_max_f32_e32 v64, v64, v64
	v_max_f32_e32 v65, v138, v138
	v_max_f32_e32 v64, v65, v64
	v_sub_f32_e32 v65, v138, v64
	v_exp_f32_e32 v66, v65
	v_mov_b32_e32 v138, v64
	v_pk_mul_f32 v[30:31], v[30:31], v[66:67] op_sel_hi:[1,0]
	v_pk_mul_f32 v[28:29], v[28:29], v[66:67] op_sel_hi:[1,0]
	v_pk_mul_f32 v[26:27], v[26:27], v[66:67] op_sel_hi:[1,0]
	v_pk_mul_f32 v[24:25], v[24:25], v[66:67] op_sel_hi:[1,0]
	v_pk_mul_f32 v[22:23], v[22:23], v[66:67] op_sel_hi:[1,0]
	v_pk_mul_f32 v[20:21], v[20:21], v[66:67] op_sel_hi:[1,0]
	v_pk_mul_f32 v[18:19], v[18:19], v[66:67] op_sel_hi:[1,0]
	v_pk_mul_f32 v[16:17], v[16:17], v[66:67] op_sel_hi:[1,0]
	v_pk_mul_f32 v[14:15], v[14:15], v[66:67] op_sel_hi:[1,0]
	v_pk_mul_f32 v[12:13], v[12:13], v[66:67] op_sel_hi:[1,0]
	v_pk_mul_f32 v[10:11], v[10:11], v[66:67] op_sel_hi:[1,0]
	v_pk_mul_f32 v[8:9], v[8:9], v[66:67] op_sel_hi:[1,0]
	v_pk_mul_f32 v[6:7], v[6:7], v[66:67] op_sel_hi:[1,0]
	v_pk_mul_f32 v[4:5], v[4:5], v[66:67] op_sel_hi:[1,0]
	v_pk_mul_f32 v[2:3], v[2:3], v[66:67] op_sel_hi:[1,0]
	v_pk_mul_f32 v[0:1], v[0:1], v[66:67] op_sel_hi:[1,0]
	v_mul_f32_e32 v149, v149, v66

.LBB0_2453:
	s_and_b32 s22, s27, 1
	s_mul_i32 s23, s22, 0x3400
	v_add_u32_e32 v162, s23, v145
	ds_read_b128 v[32:35], v162
	ds_read_b128 v[36:39], v162 offset:32
	s_waitcnt lgkmcnt(1)
	v_mfma_f32_32x32x16_bf16 v[48:63], v[32:35], v[84:87], 0
	s_waitcnt lgkmcnt(0)
	v_mfma_f32_32x32x16_bf16 v[48:63], v[36:39], v[80:83], v[48:63]
	ds_read_b128 v[32:35], v162 offset:64
	ds_read_b128 v[36:39], v162 offset:96
	s_waitcnt lgkmcnt(1)
	v_mfma_f32_32x32x16_bf16 v[48:63], v[32:35], v[76:79], v[48:63]
	ds_read_b128 v[32:35], v162 offset:128
	ds_read_b128 v[150:153], v162 offset:160
	s_waitcnt lgkmcnt(2)
	v_mfma_f32_32x32x16_bf16 v[48:63], v[36:39], v[72:75], v[48:63]
	s_waitcnt lgkmcnt(1)
	v_mfma_f32_32x32x16_bf16 v[48:63], v[32:35], v[68:71], v[48:63]
	ds_read_b128 v[32:35], v162 offset:6656
	ds_read_b128 v[154:157], v162 offset:6688
	s_waitcnt lgkmcnt(1)
	v_mfma_f32_32x32x16_bf16 v[32:47], v[32:35], v[84:87], 0
	s_waitcnt lgkmcnt(0)
	v_mfma_f32_32x32x16_bf16 v[32:47], v[154:157], v[80:83], v[32:47]
	ds_read_b128 v[154:157], v162 offset:6720
	ds_read_b128 v[158:161], v162 offset:6752
	s_waitcnt lgkmcnt(1)
	v_mfma_f32_32x32x16_bf16 v[32:47], v[154:157], v[76:79], v[32:47]
	s_waitcnt lgkmcnt(0)
	v_mfma_f32_32x32x16_bf16 v[32:47], v[158:161], v[72:75], v[32:47]
	ds_read_b128 v[154:157], v162 offset:6784
	ds_read_b128 v[158:161], v162 offset:6816
	s_waitcnt lgkmcnt(1)
	v_mfma_f32_32x32x16_bf16 v[32:47], v[154:157], v[68:71], v[32:47]
	s_waitcnt lgkmcnt(0)
	v_mfma_f32_32x32x16_bf16 v[32:47], v[158:161], v[64:67], v[32:47]
	v_mfma_f32_32x32x16_bf16 v[48:63], v[150:153], v[64:67], v[48:63]
	v_lshl_add_u64 v[184:185], s[6:7], 0, v[136:137]
	v_add_co_u32_e32 v186, vcc, 0xf220000, v184
	s_nop 0
	v_addc_co_u32_e32 v187, vcc, 0, v185, vcc
	v_add_co_u32_e32 v184, vcc, 0xf230000, v184
	s_nop 1
	v_addc_co_u32_e32 v185, vcc, 0, v185, vcc
	global_load_dwordx4 v[96:99], v[186:187], off
	global_load_dwordx4 v[100:103], v[184:185], off
	v_lshl_add_u64 v[184:185], s[6:7], 0, v[132:133]
	v_lshl_add_u64 v[186:187], s[6:7], 0, v[134:135]
	global_load_dwordx4 v[104:107], v[184:185], off
	global_load_dwordx4 v[88:91], v[186:187], off offset:-2048
	global_load_dwordx4 v[92:95], v[186:187], off
	v_max_f32_e32 v154, v32, v32
	v_max_f32_e32 v150, v48, v48
	v_max_f32_e32 v150, v150, v154
	v_max3_f32 v150, v150, v49, v33
	v_max3_f32 v150, v150, v50, v34
	v_max3_f32 v150, v150, v51, v35
	v_max3_f32 v150, v150, v52, v36
	v_max3_f32 v150, v150, v53, v37
	v_max3_f32 v150, v150, v54, v38
	v_max3_f32 v150, v150, v55, v39
	v_max3_f32 v150, v150, v56, v40
	v_max3_f32 v150, v150, v57, v41
	v_max3_f32 v150, v150, v58, v42
	v_max3_f32 v150, v150, v59, v43
	v_max3_f32 v150, v150, v60, v44
	v_max3_f32 v150, v150, v61, v45
	v_max3_f32 v150, v150, v62, v46
	v_max3_f32 v150, v150, v63, v47
	v_mov_b32_e32 v151, v150
	s_nop 1
	v_permlane32_swap_b32_e32 v150, v151
	s_nop 0
	v_max_f32_e32 v150, v150, v151
	v_mul_f32_e32 v150, 0x3e16c740, v150
	v_add_f32_e32 v151, 0x41000000, v138
	v_cmp_gt_f32_e32 vcc, v150, v151
	s_cbranch_vccz .LBB0_2452
	v_max_f32_e32 v150, v150, v150
	v_max_f32_e32 v151, v138, v138
	v_max_f32_e32 v150, v151, v150
	v_sub_f32_e32 v138, v138, v150
	v_exp_f32_e32 v138, v138
	s_nop 0
	v_pk_mul_f32 v[30:31], v[30:31], v[138:139] op_sel_hi:[1,0]
	v_pk_mul_f32 v[28:29], v[28:29], v[138:139] op_sel_hi:[1,0]
	v_pk_mul_f32 v[26:27], v[26:27], v[138:139] op_sel_hi:[1,0]
	v_pk_mul_f32 v[24:25], v[24:25], v[138:139] op_sel_hi:[1,0]
	v_pk_mul_f32 v[22:23], v[22:23], v[138:139] op_sel_hi:[1,0]
	v_pk_mul_f32 v[20:21], v[20:21], v[138:139] op_sel_hi:[1,0]
	v_pk_mul_f32 v[18:19], v[18:19], v[138:139] op_sel_hi:[1,0]
	v_pk_mul_f32 v[16:17], v[16:17], v[138:139] op_sel_hi:[1,0]
	v_pk_mul_f32 v[14:15], v[14:15], v[138:139] op_sel_hi:[1,0]
	v_pk_mul_f32 v[12:13], v[12:13], v[138:139] op_sel_hi:[1,0]
	v_pk_mul_f32 v[10:11], v[10:11], v[138:139] op_sel_hi:[1,0]
	v_pk_mul_f32 v[8:9], v[8:9], v[138:139] op_sel_hi:[1,0]
	v_pk_mul_f32 v[6:7], v[6:7], v[138:139] op_sel_hi:[1,0]
	v_pk_mul_f32 v[4:5], v[4:5], v[138:139] op_sel_hi:[1,0]
	v_pk_mul_f32 v[2:3], v[2:3], v[138:139] op_sel_hi:[1,0]
	v_pk_mul_f32 v[0:1], v[0:1], v[138:139] op_sel_hi:[1,0]
	v_mul_f32_e32 v149, v149, v138
	v_mov_b32_e32 v138, v150
	s_branch .LBB0_2452

.LBB0_3091:
	ds_read_b128 v[76:79], v203 offset:62464
	ds_read_b128 v[80:83], v203 offset:62480
	ds_read_b128 v[216:219], v203 offset:62496
	ds_read_b128 v[174:177], v203 offset:62512
	s_waitcnt lgkmcnt(3)
	v_fma_f32 v115, v76, v120, v134
	v_fma_f32 v117, v76, v154, v135
	v_fmac_f32_e32 v115, v77, v122
	v_fmac_f32_e32 v117, v77, v156
	v_fmac_f32_e32 v115, v78, v118
	v_fmac_f32_e32 v117, v78, v158
	v_fmac_f32_e32 v115, v79, v124
	v_fmac_f32_e32 v117, v79, v160
	ds_read_b128 v[76:79], v203 offset:62528
	s_waitcnt lgkmcnt(3)
	v_fmac_f32_e32 v115, v80, v121
	v_fmac_f32_e32 v117, v80, v155
	v_fmac_f32_e32 v115, v81, v123
	v_fmac_f32_e32 v117, v81, v157
	v_fmac_f32_e32 v115, v82, v119
	v_fmac_f32_e32 v117, v82, v159
	v_fmac_f32_e32 v115, v83, v125
	v_fmac_f32_e32 v117, v83, v161
	ds_read_b128 v[80:83], v203 offset:62544
	s_waitcnt lgkmcnt(3)
	v_fmac_f32_e32 v115, v216, v126
	v_fmac_f32_e32 v117, v216, v146
	v_fmac_f32_e32 v115, v217, v128
	v_fmac_f32_e32 v117, v217, v148
	v_fmac_f32_e32 v115, v218, v130
	v_fmac_f32_e32 v117, v218, v150
	v_fmac_f32_e32 v115, v219, v132
	v_fmac_f32_e32 v117, v219, v152
	ds_read_b128 v[216:219], v203 offset:62560
	s_waitcnt lgkmcnt(3)
	v_fmac_f32_e32 v115, v174, v127
	v_fmac_f32_e32 v117, v174, v147
	v_fmac_f32_e32 v115, v175, v129
	v_fmac_f32_e32 v117, v175, v149
	v_fmac_f32_e32 v115, v176, v131
	v_fmac_f32_e32 v117, v176, v151
	v_fmac_f32_e32 v115, v177, v133
	v_fmac_f32_e32 v117, v177, v153
	ds_read_b128 v[174:177], v203 offset:62576
	s_waitcnt lgkmcnt(3)
	v_fma_f32 v222, v76, v120, v134
	v_fma_f32 v223, v76, v154, v135
	v_mul_f32_e64 v178, |v115|, s86
	v_fmac_f32_e32 v222, v77, v122
	v_fmac_f32_e32 v223, v77, v156
	v_mul_f32_e64 v179, |v117|, s86
	v_fmac_f32_e32 v222, v78, v118
	v_fmac_f32_e32 v223, v78, v158
	v_exp_f32_e32 v178, v178
	v_fmac_f32_e32 v222, v79, v124
	v_fmac_f32_e32 v223, v79, v160
	v_exp_f32_e32 v179, v179
	ds_read_b128 v[76:79], v203 offset:62592
	s_waitcnt lgkmcnt(3)
	v_fmac_f32_e32 v222, v80, v121
	v_fmac_f32_e32 v223, v80, v155
	v_max_f32_e64 v115, -v115, 0
	v_fmac_f32_e32 v222, v81, v123
	v_fmac_f32_e32 v223, v81, v157
	v_max_f32_e64 v117, -v117, 0
	v_fmac_f32_e32 v222, v82, v119
	v_fmac_f32_e32 v223, v82, v159
	v_add_f32_e32 v178, 1.0, v178
	v_fmac_f32_e32 v222, v83, v125
	v_fmac_f32_e32 v223, v83, v161
	v_add_f32_e32 v179, 1.0, v179
	ds_read_b128 v[80:83], v203 offset:62608
	s_waitcnt lgkmcnt(3)
	v_fmac_f32_e32 v222, v216, v126
	v_fmac_f32_e32 v223, v216, v146
	v_log_f32_e32 v178, v178
	v_fmac_f32_e32 v222, v217, v128
	v_fmac_f32_e32 v223, v217, v148
	v_log_f32_e32 v179, v179
	v_fmac_f32_e32 v222, v218, v130
	v_fmac_f32_e32 v223, v218, v150
	v_fmac_f32_e32 v115, 0x3f317217, v178
	v_fmac_f32_e32 v222, v219, v132
	v_fmac_f32_e32 v223, v219, v152
	v_fmac_f32_e32 v117, 0x3f317217, v179
	ds_read_b128 v[216:219], v203 offset:62624
	s_waitcnt lgkmcnt(3)
	v_fmac_f32_e32 v222, v174, v127
	v_fmac_f32_e32 v223, v174, v147
	v_mul_f32_e32 v115, 0xbdb8aa3b, v115
	v_fmac_f32_e32 v222, v175, v129
	v_fmac_f32_e32 v223, v175, v149
	v_mul_f32_e32 v117, 0xbdb8aa3b, v117
	v_fmac_f32_e32 v222, v176, v131
	v_fmac_f32_e32 v223, v176, v151
	v_exp_f32_e32 v84, v115
	v_fmac_f32_e32 v222, v177, v133
	v_fmac_f32_e32 v223, v177, v153
	v_exp_f32_e32 v85, v117
	ds_read_b128 v[174:177], v203 offset:62640
	s_waitcnt lgkmcnt(3)
	v_fma_f32 v115, v76, v120, v134
	v_fma_f32 v117, v76, v154, v135
	v_mul_f32_e64 v224, |v222|, s86
	v_fmac_f32_e32 v115, v77, v122
	v_fmac_f32_e32 v117, v77, v156
	v_mul_f32_e64 v225, |v223|, s86
	v_mov_b32_e32 v220, v84
	v_mov_b32_e32 v221, v85
	v_fmac_f32_e32 v115, v78, v118
	v_fmac_f32_e32 v117, v78, v158
	v_exp_f32_e32 v224, v224
	v_fmac_f32_e32 v115, v79, v124
	v_fmac_f32_e32 v117, v79, v160
	v_exp_f32_e32 v225, v225
	ds_read_b128 v[76:79], v203 offset:62656
	s_waitcnt lgkmcnt(3)
	v_fmac_f32_e32 v115, v80, v121
	v_fmac_f32_e32 v117, v80, v155
	v_max_f32_e64 v222, -v222, 0
	v_fmac_f32_e32 v115, v81, v123
	v_fmac_f32_e32 v117, v81, v157
	v_max_f32_e64 v223, -v223, 0
	v_fmac_f32_e32 v115, v82, v119
	v_fmac_f32_e32 v117, v82, v159
	v_add_f32_e32 v224, 1.0, v224
	v_fmac_f32_e32 v115, v83, v125
	v_fmac_f32_e32 v117, v83, v161
	v_add_f32_e32 v225, 1.0, v225
	ds_read_b128 v[80:83], v203 offset:62672
	s_waitcnt lgkmcnt(3)
	v_fmac_f32_e32 v115, v216, v126
	v_fmac_f32_e32 v117, v216, v146
	v_log_f32_e32 v224, v224
	v_fmac_f32_e32 v115, v217, v128
	v_fmac_f32_e32 v117, v217, v148
	v_log_f32_e32 v225, v225
	v_fmac_f32_e32 v115, v218, v130
	v_fmac_f32_e32 v117, v218, v150
	v_fmac_f32_e32 v222, 0x3f317217, v224
	v_fmac_f32_e32 v115, v219, v132
	v_fmac_f32_e32 v117, v219, v152
	v_fmac_f32_e32 v223, 0x3f317217, v225
	ds_read_b128 v[216:219], v203 offset:62688
	s_waitcnt lgkmcnt(3)
	v_fmac_f32_e32 v115, v174, v127
	v_fmac_f32_e32 v117, v174, v147
	v_mul_f32_e32 v222, 0xbdb8aa3b, v222
	v_fmac_f32_e32 v115, v175, v129
	v_fmac_f32_e32 v117, v175, v149
	v_mul_f32_e32 v223, 0xbdb8aa3b, v223
	v_fmac_f32_e32 v115, v176, v131
	v_fmac_f32_e32 v117, v176, v151
	v_exp_f32_e32 v86, v222
	v_fmac_f32_e32 v115, v177, v133
	v_fmac_f32_e32 v117, v177, v153
	v_exp_f32_e32 v87, v223
	ds_read_b128 v[174:177], v203 offset:62704
	s_waitcnt lgkmcnt(3)
	v_fma_f32 v222, v76, v120, v134
	v_fma_f32 v223, v76, v154, v135
	v_mul_f32_e64 v178, |v115|, s86
	v_fmac_f32_e32 v222, v77, v122
	v_fmac_f32_e32 v223, v77, v156
	v_mul_f32_e64 v179, |v117|, s86
	v_pk_mul_f32 v[220:221], v[220:221], v[86:87]
	v_fmac_f32_e32 v222, v78, v118
	v_fmac_f32_e32 v223, v78, v158
	v_exp_f32_e32 v178, v178
	v_fmac_f32_e32 v222, v79, v124
	v_fmac_f32_e32 v223, v79, v160
	v_exp_f32_e32 v179, v179
	ds_read_b128 v[76:79], v203 offset:62720
	s_waitcnt lgkmcnt(3)
	v_fmac_f32_e32 v222, v80, v121
	v_fmac_f32_e32 v223, v80, v155
	v_max_f32_e64 v115, -v115, 0
	v_fmac_f32_e32 v222, v81, v123
	v_fmac_f32_e32 v223, v81, v157
	v_max_f32_e64 v117, -v117, 0
	v_fmac_f32_e32 v222, v82, v119
	v_fmac_f32_e32 v223, v82, v159
	v_add_f32_e32 v178, 1.0, v178
	v_fmac_f32_e32 v222, v83, v125
	v_fmac_f32_e32 v223, v83, v161
	v_add_f32_e32 v179, 1.0, v179
	ds_read_b128 v[80:83], v203 offset:62736
	s_waitcnt lgkmcnt(3)
	v_fmac_f32_e32 v222, v216, v126
	v_fmac_f32_e32 v223, v216, v146
	v_log_f32_e32 v178, v178
	v_fmac_f32_e32 v222, v217, v128
	v_fmac_f32_e32 v223, v217, v148
	v_log_f32_e32 v179, v179
	v_fmac_f32_e32 v222, v218, v130
	v_fmac_f32_e32 v223, v218, v150
	v_fmac_f32_e32 v115, 0x3f317217, v178
	v_fmac_f32_e32 v222, v219, v132
	v_fmac_f32_e32 v223, v219, v152
	v_fmac_f32_e32 v117, 0x3f317217, v179
	ds_read_b128 v[216:219], v203 offset:62752
	s_waitcnt lgkmcnt(3)
	v_fmac_f32_e32 v222, v174, v127
	v_fmac_f32_e32 v223, v174, v147
	v_mul_f32_e32 v115, 0xbdb8aa3b, v115
	v_fmac_f32_e32 v222, v175, v129
	v_fmac_f32_e32 v223, v175, v149
	v_mul_f32_e32 v117, 0xbdb8aa3b, v117
	v_fmac_f32_e32 v222, v176, v131
	v_fmac_f32_e32 v223, v176, v151
	v_exp_f32_e32 v88, v115
	v_fmac_f32_e32 v222, v177, v133
	v_fmac_f32_e32 v223, v177, v153
	v_exp_f32_e32 v89, v117
	ds_read_b128 v[174:177], v203 offset:62768
	s_waitcnt lgkmcnt(3)
	v_fma_f32 v115, v76, v120, v134
	v_fma_f32 v117, v76, v154, v135
	v_mul_f32_e64 v224, |v222|, s86
	v_fmac_f32_e32 v115, v77, v122
	v_fmac_f32_e32 v117, v77, v156
	v_mul_f32_e64 v225, |v223|, s86
	v_pk_mul_f32 v[220:221], v[220:221], v[88:89]
	v_fmac_f32_e32 v115, v78, v118
	v_fmac_f32_e32 v117, v78, v158
	v_exp_f32_e32 v224, v224
	v_fmac_f32_e32 v115, v79, v124
	v_fmac_f32_e32 v117, v79, v160
	v_exp_f32_e32 v225, v225
	ds_read_b128 v[76:79], v203 offset:62784
	s_waitcnt lgkmcnt(3)
	v_fmac_f32_e32 v115, v80, v121
	v_fmac_f32_e32 v117, v80, v155
	v_max_f32_e64 v222, -v222, 0
	v_fmac_f32_e32 v115, v81, v123
	v_fmac_f32_e32 v117, v81, v157
	v_max_f32_e64 v223, -v223, 0
	v_fmac_f32_e32 v115, v82, v119
	v_fmac_f32_e32 v117, v82, v159
	v_add_f32_e32 v224, 1.0, v224
	v_fmac_f32_e32 v115, v83, v125
	v_fmac_f32_e32 v117, v83, v161
	v_add_f32_e32 v225, 1.0, v225
	ds_read_b128 v[80:83], v203 offset:62800
	s_waitcnt lgkmcnt(3)
	v_fmac_f32_e32 v115, v216, v126
	v_fmac_f32_e32 v117, v216, v146
	v_log_f32_e32 v224, v224
	v_fmac_f32_e32 v115, v217, v128
	v_fmac_f32_e32 v117, v217, v148
	v_log_f32_e32 v225, v225
	v_fmac_f32_e32 v115, v218, v130
	v_fmac_f32_e32 v117, v218, v150
	v_fmac_f32_e32 v222, 0x3f317217, v224
	v_fmac_f32_e32 v115, v219, v132
	v_fmac_f32_e32 v117, v219, v152
	v_fmac_f32_e32 v223, 0x3f317217, v225
	ds_read_b128 v[216:219], v203 offset:62816
	s_waitcnt lgkmcnt(3)
	v_fmac_f32_e32 v115, v174, v127
	v_fmac_f32_e32 v117, v174, v147
	v_mul_f32_e32 v222, 0xbdb8aa3b, v222
	v_fmac_f32_e32 v115, v175, v129
	v_fmac_f32_e32 v117, v175, v149
	v_mul_f32_e32 v223, 0xbdb8aa3b, v223
	v_fmac_f32_e32 v115, v176, v131
	v_fmac_f32_e32 v117, v176, v151
	v_exp_f32_e32 v90, v222
	v_fmac_f32_e32 v115, v177, v133
	v_fmac_f32_e32 v117, v177, v153
	v_exp_f32_e32 v91, v223
	ds_read_b128 v[174:177], v203 offset:62832
	s_waitcnt lgkmcnt(3)
	v_fma_f32 v222, v76, v120, v134
	v_fma_f32 v223, v76, v154, v135
	v_mul_f32_e64 v178, |v115|, s86
	v_fmac_f32_e32 v222, v77, v122
	v_fmac_f32_e32 v223, v77, v156
	v_mul_f32_e64 v179, |v117|, s86
	v_pk_mul_f32 v[220:221], v[220:221], v[90:91]
	v_fmac_f32_e32 v222, v78, v118
	v_fmac_f32_e32 v223, v78, v158
	v_exp_f32_e32 v178, v178
	v_fmac_f32_e32 v222, v79, v124
	v_fmac_f32_e32 v223, v79, v160
	v_exp_f32_e32 v179, v179
	ds_read_b128 v[76:79], v203 offset:62848
	s_waitcnt lgkmcnt(3)
	v_fmac_f32_e32 v222, v80, v121
	v_fmac_f32_e32 v223, v80, v155
	v_max_f32_e64 v115, -v115, 0
	v_fmac_f32_e32 v222, v81, v123
	v_fmac_f32_e32 v223, v81, v157
	v_max_f32_e64 v117, -v117, 0
	v_fmac_f32_e32 v222, v82, v119
	v_fmac_f32_e32 v223, v82, v159
	v_add_f32_e32 v178, 1.0, v178
	v_fmac_f32_e32 v222, v83, v125
	v_fmac_f32_e32 v223, v83, v161
	v_add_f32_e32 v179, 1.0, v179
	ds_read_b128 v[80:83], v203 offset:62864
	s_waitcnt lgkmcnt(3)
	v_fmac_f32_e32 v222, v216, v126
	v_fmac_f32_e32 v223, v216, v146
	v_log_f32_e32 v178, v178
	v_fmac_f32_e32 v222, v217, v128
	v_fmac_f32_e32 v223, v217, v148
	v_log_f32_e32 v179, v179
	v_fmac_f32_e32 v222, v218, v130
	v_fmac_f32_e32 v223, v218, v150
	v_fmac_f32_e32 v115, 0x3f317217, v178
	v_fmac_f32_e32 v222, v219, v132
	v_fmac_f32_e32 v223, v219, v152
	v_fmac_f32_e32 v117, 0x3f317217, v179
	ds_read_b128 v[216:219], v203 offset:62880
	s_waitcnt lgkmcnt(3)
	v_fmac_f32_e32 v222, v174, v127
	v_fmac_f32_e32 v223, v174, v147
	v_mul_f32_e32 v115, 0xbdb8aa3b, v115
	v_fmac_f32_e32 v222, v175, v129
	v_fmac_f32_e32 v223, v175, v149
	v_mul_f32_e32 v117, 0xbdb8aa3b, v117
	v_fmac_f32_e32 v222, v176, v131
	v_fmac_f32_e32 v223, v176, v151
	v_exp_f32_e32 v92, v115
	v_fmac_f32_e32 v222, v177, v133
	v_fmac_f32_e32 v223, v177, v153
	v_exp_f32_e32 v93, v117
	ds_read_b128 v[174:177], v203 offset:62896
	s_waitcnt lgkmcnt(3)
	v_fma_f32 v115, v76, v120, v134
	v_fma_f32 v117, v76, v154, v135
	v_mul_f32_e64 v224, |v222|, s86
	v_fmac_f32_e32 v115, v77, v122
	v_fmac_f32_e32 v117, v77, v156
	v_mul_f32_e64 v225, |v223|, s86
	v_pk_mul_f32 v[220:221], v[220:221], v[92:93]
	v_fmac_f32_e32 v115, v78, v118
	v_fmac_f32_e32 v117, v78, v158
	v_exp_f32_e32 v224, v224
	v_fmac_f32_e32 v115, v79, v124
	v_fmac_f32_e32 v117, v79, v160
	v_exp_f32_e32 v225, v225
	ds_read_b128 v[76:79], v203 offset:62912
	s_waitcnt lgkmcnt(3)
	v_fmac_f32_e32 v115, v80, v121
	v_fmac_f32_e32 v117, v80, v155
	v_max_f32_e64 v222, -v222, 0
	v_fmac_f32_e32 v115, v81, v123
	v_fmac_f32_e32 v117, v81, v157
	v_max_f32_e64 v223, -v223, 0
	v_fmac_f32_e32 v115, v82, v119
	v_fmac_f32_e32 v117, v82, v159
	v_add_f32_e32 v224, 1.0, v224
	v_fmac_f32_e32 v115, v83, v125
	v_fmac_f32_e32 v117, v83, v161
	v_add_f32_e32 v225, 1.0, v225
	ds_read_b128 v[80:83], v203 offset:62928
	s_waitcnt lgkmcnt(3)
	v_fmac_f32_e32 v115, v216, v126
	v_fmac_f32_e32 v117, v216, v146
	v_log_f32_e32 v224, v224
	v_fmac_f32_e32 v115, v217, v128
	v_fmac_f32_e32 v117, v217, v148
	v_log_f32_e32 v225, v225
	v_fmac_f32_e32 v115, v218, v130
	v_fmac_f32_e32 v117, v218, v150
	v_fmac_f32_e32 v222, 0x3f317217, v224
	v_fmac_f32_e32 v115, v219, v132
	v_fmac_f32_e32 v117, v219, v152
	v_fmac_f32_e32 v223, 0x3f317217, v225
	ds_read_b128 v[216:219], v203 offset:62944
	s_waitcnt lgkmcnt(3)
	v_fmac_f32_e32 v115, v174, v127
	v_fmac_f32_e32 v117, v174, v147
	v_mul_f32_e32 v222, 0xbdb8aa3b, v222
	v_fmac_f32_e32 v115, v175, v129
	v_fmac_f32_e32 v117, v175, v149
	v_mul_f32_e32 v223, 0xbdb8aa3b, v223
	v_fmac_f32_e32 v115, v176, v131
	v_fmac_f32_e32 v117, v176, v151
	v_exp_f32_e32 v94, v222
	v_fmac_f32_e32 v115, v177, v133
	v_fmac_f32_e32 v117, v177, v153
	v_exp_f32_e32 v95, v223
	ds_read_b128 v[174:177], v203 offset:62960
	s_waitcnt lgkmcnt(3)
	v_fma_f32 v222, v76, v120, v134
	v_fma_f32 v223, v76, v154, v135
	v_mul_f32_e64 v178, |v115|, s86
	v_fmac_f32_e32 v222, v77, v122
	v_fmac_f32_e32 v223, v77, v156
	v_mul_f32_e64 v179, |v117|, s86
	v_pk_mul_f32 v[220:221], v[220:221], v[94:95]
	v_fmac_f32_e32 v222, v78, v118
	v_fmac_f32_e32 v223, v78, v158
	v_exp_f32_e32 v178, v178
	v_fmac_f32_e32 v222, v79, v124
	v_fmac_f32_e32 v223, v79, v160
	v_exp_f32_e32 v179, v179
	ds_read_b128 v[76:79], v203 offset:62976
	s_waitcnt lgkmcnt(3)
	v_fmac_f32_e32 v222, v80, v121
	v_fmac_f32_e32 v223, v80, v155
	v_max_f32_e64 v115, -v115, 0
	v_fmac_f32_e32 v222, v81, v123
	v_fmac_f32_e32 v223, v81, v157
	v_max_f32_e64 v117, -v117, 0
	v_fmac_f32_e32 v222, v82, v119
	v_fmac_f32_e32 v223, v82, v159
	v_add_f32_e32 v178, 1.0, v178
	v_fmac_f32_e32 v222, v83, v125
	v_fmac_f32_e32 v223, v83, v161
	v_add_f32_e32 v179, 1.0, v179
	ds_read_b128 v[80:83], v203 offset:62992
	s_waitcnt lgkmcnt(3)
	v_fmac_f32_e32 v222, v216, v126
	v_fmac_f32_e32 v223, v216, v146
	v_log_f32_e32 v178, v178
	v_fmac_f32_e32 v222, v217, v128
	v_fmac_f32_e32 v223, v217, v148
	v_log_f32_e32 v179, v179
	v_fmac_f32_e32 v222, v218, v130
	v_fmac_f32_e32 v223, v218, v150
	v_fmac_f32_e32 v115, 0x3f317217, v178
	v_fmac_f32_e32 v222, v219, v132
	v_fmac_f32_e32 v223, v219, v152
	v_fmac_f32_e32 v117, 0x3f317217, v179
	ds_read_b128 v[216:219], v203 offset:63008
	s_waitcnt lgkmcnt(3)
	v_fmac_f32_e32 v222, v174, v127
	v_fmac_f32_e32 v223, v174, v147
	v_mul_f32_e32 v115, 0xbdb8aa3b, v115
	v_fmac_f32_e32 v222, v175, v129
	v_fmac_f32_e32 v223, v175, v149
	v_mul_f32_e32 v117, 0xbdb8aa3b, v117
	v_fmac_f32_e32 v222, v176, v131
	v_fmac_f32_e32 v223, v176, v151
	v_exp_f32_e32 v96, v115
	v_fmac_f32_e32 v222, v177, v133
	v_fmac_f32_e32 v223, v177, v153
	v_exp_f32_e32 v97, v117
	ds_read_b128 v[174:177], v203 offset:63024
	s_waitcnt lgkmcnt(3)
	v_fma_f32 v115, v76, v120, v134
	v_fma_f32 v117, v76, v154, v135
	v_mul_f32_e64 v224, |v222|, s86
	v_fmac_f32_e32 v115, v77, v122
	v_fmac_f32_e32 v117, v77, v156
	v_mul_f32_e64 v225, |v223|, s86
	v_pk_mul_f32 v[220:221], v[220:221], v[96:97]
	v_fmac_f32_e32 v115, v78, v118
	v_fmac_f32_e32 v117, v78, v158
	v_exp_f32_e32 v224, v224
	v_fmac_f32_e32 v115, v79, v124
	v_fmac_f32_e32 v117, v79, v160
	v_exp_f32_e32 v225, v225
	ds_read_b128 v[76:79], v203 offset:63040
	s_waitcnt lgkmcnt(3)
	v_fmac_f32_e32 v115, v80, v121
	v_fmac_f32_e32 v117, v80, v155
	v_max_f32_e64 v222, -v222, 0
	v_fmac_f32_e32 v115, v81, v123
	v_fmac_f32_e32 v117, v81, v157
	v_max_f32_e64 v223, -v223, 0
	v_fmac_f32_e32 v115, v82, v119
	v_fmac_f32_e32 v117, v82, v159
	v_add_f32_e32 v224, 1.0, v224
	v_fmac_f32_e32 v115, v83, v125
	v_fmac_f32_e32 v117, v83, v161
	v_add_f32_e32 v225, 1.0, v225
	ds_read_b128 v[80:83], v203 offset:63056
	s_waitcnt lgkmcnt(3)
	v_fmac_f32_e32 v115, v216, v126
	v_fmac_f32_e32 v117, v216, v146
	v_log_f32_e32 v224, v224
	v_fmac_f32_e32 v115, v217, v128
	v_fmac_f32_e32 v117, v217, v148
	v_log_f32_e32 v225, v225
	v_fmac_f32_e32 v115, v218, v130
	v_fmac_f32_e32 v117, v218, v150
	v_fmac_f32_e32 v222, 0x3f317217, v224
	v_fmac_f32_e32 v115, v219, v132
	v_fmac_f32_e32 v117, v219, v152
	v_fmac_f32_e32 v223, 0x3f317217, v225
	ds_read_b128 v[216:219], v203 offset:63072
	s_waitcnt lgkmcnt(3)
	v_fmac_f32_e32 v115, v174, v127
	v_fmac_f32_e32 v117, v174, v147
	v_mul_f32_e32 v222, 0xbdb8aa3b, v222
	v_fmac_f32_e32 v115, v175, v129
	v_fmac_f32_e32 v117, v175, v149
	v_mul_f32_e32 v223, 0xbdb8aa3b, v223
	v_fmac_f32_e32 v115, v176, v131
	v_fmac_f32_e32 v117, v176, v151
	v_exp_f32_e32 v98, v222
	v_fmac_f32_e32 v115, v177, v133
	v_fmac_f32_e32 v117, v177, v153
	v_exp_f32_e32 v99, v223
	ds_read_b128 v[174:177], v203 offset:63088
	s_waitcnt lgkmcnt(3)
	v_fma_f32 v222, v76, v120, v134
	v_fma_f32 v223, v76, v154, v135
	v_mul_f32_e64 v178, |v115|, s86
	v_fmac_f32_e32 v222, v77, v122
	v_fmac_f32_e32 v223, v77, v156
	v_mul_f32_e64 v179, |v117|, s86
	v_pk_mul_f32 v[220:221], v[220:221], v[98:99]
	v_fmac_f32_e32 v222, v78, v118
	v_fmac_f32_e32 v223, v78, v158
	v_exp_f32_e32 v178, v178
	v_fmac_f32_e32 v222, v79, v124
	v_fmac_f32_e32 v223, v79, v160
	v_exp_f32_e32 v179, v179
	ds_read_b128 v[76:79], v203 offset:63104
	s_waitcnt lgkmcnt(3)
	v_fmac_f32_e32 v222, v80, v121
	v_fmac_f32_e32 v223, v80, v155
	v_max_f32_e64 v115, -v115, 0
	v_fmac_f32_e32 v222, v81, v123
	v_fmac_f32_e32 v223, v81, v157
	v_max_f32_e64 v117, -v117, 0
	v_fmac_f32_e32 v222, v82, v119
	v_fmac_f32_e32 v223, v82, v159
	v_add_f32_e32 v178, 1.0, v178
	v_fmac_f32_e32 v222, v83, v125
	v_fmac_f32_e32 v223, v83, v161
	v_add_f32_e32 v179, 1.0, v179
	ds_read_b128 v[80:83], v203 offset:63120
	s_waitcnt lgkmcnt(3)
	v_fmac_f32_e32 v222, v216, v126
	v_fmac_f32_e32 v223, v216, v146
	v_log_f32_e32 v178, v178
	v_fmac_f32_e32 v222, v217, v128
	v_fmac_f32_e32 v223, v217, v148
	v_log_f32_e32 v179, v179
	v_fmac_f32_e32 v222, v218, v130
	v_fmac_f32_e32 v223, v218, v150
	v_fmac_f32_e32 v115, 0x3f317217, v178
	v_fmac_f32_e32 v222, v219, v132
	v_fmac_f32_e32 v223, v219, v152
	v_fmac_f32_e32 v117, 0x3f317217, v179
	ds_read_b128 v[216:219], v203 offset:63136
	s_waitcnt lgkmcnt(3)
	v_fmac_f32_e32 v222, v174, v127
	v_fmac_f32_e32 v223, v174, v147
	v_mul_f32_e32 v115, 0xbdb8aa3b, v115
	v_fmac_f32_e32 v222, v175, v129
	v_fmac_f32_e32 v223, v175, v149
	v_mul_f32_e32 v117, 0xbdb8aa3b, v117
	v_fmac_f32_e32 v222, v176, v131
	v_fmac_f32_e32 v223, v176, v151
	v_exp_f32_e32 v162, v115
	v_fmac_f32_e32 v222, v177, v133
	v_fmac_f32_e32 v223, v177, v153
	v_exp_f32_e32 v163, v117
	ds_read_b128 v[174:177], v203 offset:63152
	s_waitcnt lgkmcnt(3)
	v_fma_f32 v115, v76, v120, v134
	v_fma_f32 v117, v76, v154, v135
	v_mul_f32_e64 v224, |v222|, s86
	v_fmac_f32_e32 v115, v77, v122
	v_fmac_f32_e32 v117, v77, v156
	v_mul_f32_e64 v225, |v223|, s86
	v_pk_mul_f32 v[220:221], v[220:221], v[162:163]
	v_fmac_f32_e32 v115, v78, v118
	v_fmac_f32_e32 v117, v78, v158
	v_exp_f32_e32 v224, v224
	v_fmac_f32_e32 v115, v79, v124
	v_fmac_f32_e32 v117, v79, v160
	v_exp_f32_e32 v225, v225
	ds_read_b128 v[76:79], v203 offset:63168
	s_waitcnt lgkmcnt(3)
	v_fmac_f32_e32 v115, v80, v121
	v_fmac_f32_e32 v117, v80, v155
	v_max_f32_e64 v222, -v222, 0
	v_fmac_f32_e32 v115, v81, v123
	v_fmac_f32_e32 v117, v81, v157
	v_max_f32_e64 v223, -v223, 0
	v_fmac_f32_e32 v115, v82, v119
	v_fmac_f32_e32 v117, v82, v159
	v_add_f32_e32 v224, 1.0, v224
	v_fmac_f32_e32 v115, v83, v125
	v_fmac_f32_e32 v117, v83, v161
	v_add_f32_e32 v225, 1.0, v225
	ds_read_b128 v[80:83], v203 offset:63184
	s_waitcnt lgkmcnt(3)
	v_fmac_f32_e32 v115, v216, v126
	v_fmac_f32_e32 v117, v216, v146
	v_log_f32_e32 v224, v224
	v_fmac_f32_e32 v115, v217, v128
	v_fmac_f32_e32 v117, v217, v148
	v_log_f32_e32 v225, v225
	v_fmac_f32_e32 v115, v218, v130
	v_fmac_f32_e32 v117, v218, v150
	v_fmac_f32_e32 v222, 0x3f317217, v224
	v_fmac_f32_e32 v115, v219, v132
	v_fmac_f32_e32 v117, v219, v152
	v_fmac_f32_e32 v223, 0x3f317217, v225
	ds_read_b128 v[216:219], v203 offset:63200
	s_waitcnt lgkmcnt(3)
	v_fmac_f32_e32 v115, v174, v127
	v_fmac_f32_e32 v117, v174, v147
	v_mul_f32_e32 v222, 0xbdb8aa3b, v222
	v_fmac_f32_e32 v115, v175, v129
	v_fmac_f32_e32 v117, v175, v149
	v_mul_f32_e32 v223, 0xbdb8aa3b, v223
	v_fmac_f32_e32 v115, v176, v131
	v_fmac_f32_e32 v117, v176, v151
	v_exp_f32_e32 v164, v222
	v_fmac_f32_e32 v115, v177, v133
	v_fmac_f32_e32 v117, v177, v153
	v_exp_f32_e32 v165, v223
	ds_read_b128 v[174:177], v203 offset:63216
	s_waitcnt lgkmcnt(3)
	v_fma_f32 v222, v76, v120, v134
	v_fma_f32 v223, v76, v154, v135
	v_mul_f32_e64 v178, |v115|, s86
	v_fmac_f32_e32 v222, v77, v122
	v_fmac_f32_e32 v223, v77, v156
	v_mul_f32_e64 v179, |v117|, s86
	v_pk_mul_f32 v[220:221], v[220:221], v[164:165]
	v_fmac_f32_e32 v222, v78, v118
	v_fmac_f32_e32 v223, v78, v158
	v_exp_f32_e32 v178, v178
	v_fmac_f32_e32 v222, v79, v124
	v_fmac_f32_e32 v223, v79, v160
	v_exp_f32_e32 v179, v179
	ds_read_b128 v[76:79], v203 offset:63232
	s_waitcnt lgkmcnt(3)
	v_fmac_f32_e32 v222, v80, v121
	v_fmac_f32_e32 v223, v80, v155
	v_max_f32_e64 v115, -v115, 0
	v_fmac_f32_e32 v222, v81, v123
	v_fmac_f32_e32 v223, v81, v157
	v_max_f32_e64 v117, -v117, 0
	v_fmac_f32_e32 v222, v82, v119
	v_fmac_f32_e32 v223, v82, v159
	v_add_f32_e32 v178, 1.0, v178
	v_fmac_f32_e32 v222, v83, v125
	v_fmac_f32_e32 v223, v83, v161
	v_add_f32_e32 v179, 1.0, v179
	ds_read_b128 v[80:83], v203 offset:63248
	s_waitcnt lgkmcnt(3)
	v_fmac_f32_e32 v222, v216, v126
	v_fmac_f32_e32 v223, v216, v146
	v_log_f32_e32 v178, v178
	v_fmac_f32_e32 v222, v217, v128
	v_fmac_f32_e32 v223, v217, v148
	v_log_f32_e32 v179, v179
	v_fmac_f32_e32 v222, v218, v130
	v_fmac_f32_e32 v223, v218, v150
	v_fmac_f32_e32 v115, 0x3f317217, v178
	v_fmac_f32_e32 v222, v219, v132
	v_fmac_f32_e32 v223, v219, v152
	v_fmac_f32_e32 v117, 0x3f317217, v179
	ds_read_b128 v[216:219], v203 offset:63264
	s_waitcnt lgkmcnt(3)
	v_fmac_f32_e32 v222, v174, v127
	v_fmac_f32_e32 v223, v174, v147
	v_mul_f32_e32 v115, 0xbdb8aa3b, v115
	v_fmac_f32_e32 v222, v175, v129
	v_fmac_f32_e32 v223, v175, v149
	v_mul_f32_e32 v117, 0xbdb8aa3b, v117
	v_fmac_f32_e32 v222, v176, v131
	v_fmac_f32_e32 v223, v176, v151
	v_exp_f32_e32 v166, v115
	v_fmac_f32_e32 v222, v177, v133
	v_fmac_f32_e32 v223, v177, v153
	v_exp_f32_e32 v167, v117
	ds_read_b128 v[174:177], v203 offset:63280
	s_waitcnt lgkmcnt(3)
	v_fma_f32 v115, v76, v120, v134
	v_fma_f32 v117, v76, v154, v135
	v_mul_f32_e64 v224, |v222|, s86
	v_fmac_f32_e32 v115, v77, v122
	v_fmac_f32_e32 v117, v77, v156
	v_mul_f32_e64 v225, |v223|, s86
	v_pk_mul_f32 v[220:221], v[220:221], v[166:167]
	v_fmac_f32_e32 v115, v78, v118
	v_fmac_f32_e32 v117, v78, v158
	v_exp_f32_e32 v224, v224
	v_fmac_f32_e32 v115, v79, v124
	v_fmac_f32_e32 v117, v79, v160
	v_exp_f32_e32 v225, v225
	ds_read_b128 v[76:79], v203 offset:63296
	s_waitcnt lgkmcnt(3)
	v_fmac_f32_e32 v115, v80, v121
	v_fmac_f32_e32 v117, v80, v155
	v_max_f32_e64 v222, -v222, 0
	v_fmac_f32_e32 v115, v81, v123
	v_fmac_f32_e32 v117, v81, v157
	v_max_f32_e64 v223, -v223, 0
	v_fmac_f32_e32 v115, v82, v119
	v_fmac_f32_e32 v117, v82, v159
	v_add_f32_e32 v224, 1.0, v224
	v_fmac_f32_e32 v115, v83, v125
	v_fmac_f32_e32 v117, v83, v161
	v_add_f32_e32 v225, 1.0, v225
	ds_read_b128 v[80:83], v203 offset:63312
	s_waitcnt lgkmcnt(3)
	v_fmac_f32_e32 v115, v216, v126
	v_fmac_f32_e32 v117, v216, v146
	v_log_f32_e32 v224, v224
	v_fmac_f32_e32 v115, v217, v128
	v_fmac_f32_e32 v117, v217, v148
	v_log_f32_e32 v225, v225
	v_fmac_f32_e32 v115, v218, v130
	v_fmac_f32_e32 v117, v218, v150
	v_fmac_f32_e32 v222, 0x3f317217, v224
	v_fmac_f32_e32 v115, v219, v132
	v_fmac_f32_e32 v117, v219, v152
	v_fmac_f32_e32 v223, 0x3f317217, v225
	ds_read_b128 v[216:219], v203 offset:63328
	s_waitcnt lgkmcnt(3)
	v_fmac_f32_e32 v115, v174, v127
	v_fmac_f32_e32 v117, v174, v147
	v_mul_f32_e32 v222, 0xbdb8aa3b, v222
	v_fmac_f32_e32 v115, v175, v129
	v_fmac_f32_e32 v117, v175, v149
	v_mul_f32_e32 v223, 0xbdb8aa3b, v223
	v_fmac_f32_e32 v115, v176, v131
	v_fmac_f32_e32 v117, v176, v151
	v_exp_f32_e32 v168, v222
	v_fmac_f32_e32 v115, v177, v133
	v_fmac_f32_e32 v117, v177, v153
	v_exp_f32_e32 v169, v223
	ds_read_b128 v[174:177], v203 offset:63344
	s_waitcnt lgkmcnt(3)
	v_fma_f32 v222, v76, v120, v134
	v_fma_f32 v223, v76, v154, v135
	v_mul_f32_e64 v178, |v115|, s86
	v_fmac_f32_e32 v222, v77, v122
	v_fmac_f32_e32 v223, v77, v156
	v_mul_f32_e64 v179, |v117|, s86
	v_pk_mul_f32 v[220:221], v[220:221], v[168:169]
	v_fmac_f32_e32 v222, v78, v118
	v_fmac_f32_e32 v223, v78, v158
	v_exp_f32_e32 v178, v178
	v_fmac_f32_e32 v222, v79, v124
	v_fmac_f32_e32 v223, v79, v160
	v_exp_f32_e32 v179, v179
	ds_read_b128 v[76:79], v203 offset:63360
	s_waitcnt lgkmcnt(3)
	v_fmac_f32_e32 v222, v80, v121
	v_fmac_f32_e32 v223, v80, v155
	v_max_f32_e64 v115, -v115, 0
	v_fmac_f32_e32 v222, v81, v123
	v_fmac_f32_e32 v223, v81, v157
	v_max_f32_e64 v117, -v117, 0
	v_fmac_f32_e32 v222, v82, v119
	v_fmac_f32_e32 v223, v82, v159
	v_add_f32_e32 v178, 1.0, v178
	v_fmac_f32_e32 v222, v83, v125
	v_fmac_f32_e32 v223, v83, v161
	v_add_f32_e32 v179, 1.0, v179
	ds_read_b128 v[80:83], v203 offset:63376
	s_waitcnt lgkmcnt(3)
	v_fmac_f32_e32 v222, v216, v126
	v_fmac_f32_e32 v223, v216, v146
	v_log_f32_e32 v178, v178
	v_fmac_f32_e32 v222, v217, v128
	v_fmac_f32_e32 v223, v217, v148
	v_log_f32_e32 v179, v179
	v_fmac_f32_e32 v222, v218, v130
	v_fmac_f32_e32 v223, v218, v150
	v_fmac_f32_e32 v115, 0x3f317217, v178
	v_fmac_f32_e32 v222, v219, v132
	v_fmac_f32_e32 v223, v219, v152
	v_fmac_f32_e32 v117, 0x3f317217, v179
	ds_read_b128 v[216:219], v203 offset:63392
	s_waitcnt lgkmcnt(3)
	v_fmac_f32_e32 v222, v174, v127
	v_fmac_f32_e32 v223, v174, v147
	v_mul_f32_e32 v115, 0xbdb8aa3b, v115
	v_fmac_f32_e32 v222, v175, v129
	v_fmac_f32_e32 v223, v175, v149
	v_mul_f32_e32 v117, 0xbdb8aa3b, v117
	v_fmac_f32_e32 v222, v176, v131
	v_fmac_f32_e32 v223, v176, v151
	v_exp_f32_e32 v170, v115
	v_fmac_f32_e32 v222, v177, v133
	v_fmac_f32_e32 v223, v177, v153
	v_exp_f32_e32 v171, v117
	ds_read_b128 v[174:177], v203 offset:63408
	s_waitcnt lgkmcnt(3)
	v_fma_f32 v115, v76, v120, v134
	v_fma_f32 v117, v76, v154, v135
	v_mul_f32_e64 v224, |v222|, s86
	v_fmac_f32_e32 v115, v77, v122
	v_fmac_f32_e32 v117, v77, v156
	v_mul_f32_e64 v225, |v223|, s86
	v_pk_mul_f32 v[220:221], v[220:221], v[170:171]
	v_fmac_f32_e32 v115, v78, v118
	v_fmac_f32_e32 v117, v78, v158
	v_exp_f32_e32 v224, v224
	v_fmac_f32_e32 v115, v79, v124
	v_fmac_f32_e32 v117, v79, v160
	v_exp_f32_e32 v225, v225
	ds_read_b128 v[76:79], v203 offset:63424
	s_waitcnt lgkmcnt(3)
	v_fmac_f32_e32 v115, v80, v121
	v_fmac_f32_e32 v117, v80, v155
	v_max_f32_e64 v222, -v222, 0
	v_fmac_f32_e32 v115, v81, v123
	v_fmac_f32_e32 v117, v81, v157
	v_max_f32_e64 v223, -v223, 0
	v_fmac_f32_e32 v115, v82, v119
	v_fmac_f32_e32 v117, v82, v159
	v_add_f32_e32 v224, 1.0, v224
	v_fmac_f32_e32 v115, v83, v125
	v_fmac_f32_e32 v117, v83, v161
	v_add_f32_e32 v225, 1.0, v225
	ds_read_b128 v[80:83], v203 offset:63440
	s_waitcnt lgkmcnt(3)
	v_fmac_f32_e32 v115, v216, v126
	v_fmac_f32_e32 v117, v216, v146
	v_log_f32_e32 v224, v224
	v_fmac_f32_e32 v115, v217, v128
	v_fmac_f32_e32 v117, v217, v148
	v_log_f32_e32 v225, v225
	v_fmac_f32_e32 v115, v218, v130
	v_fmac_f32_e32 v117, v218, v150
	v_fmac_f32_e32 v222, 0x3f317217, v224
	v_fmac_f32_e32 v115, v219, v132
	v_fmac_f32_e32 v117, v219, v152
	v_fmac_f32_e32 v223, 0x3f317217, v225
	ds_read_b128 v[216:219], v203 offset:63456
	s_waitcnt lgkmcnt(3)
	v_fmac_f32_e32 v115, v174, v127
	v_fmac_f32_e32 v117, v174, v147
	v_mul_f32_e32 v222, 0xbdb8aa3b, v222
	v_fmac_f32_e32 v115, v175, v129
	v_fmac_f32_e32 v117, v175, v149
	v_mul_f32_e32 v223, 0xbdb8aa3b, v223
	v_fmac_f32_e32 v115, v176, v131
	v_fmac_f32_e32 v117, v176, v151
	v_exp_f32_e32 v172, v222
	v_fmac_f32_e32 v115, v177, v133
	v_fmac_f32_e32 v117, v177, v153
	v_exp_f32_e32 v173, v223
	s_waitcnt lgkmcnt(2)
	v_fma_f32 v222, v76, v120, v134
	v_fma_f32 v223, v76, v154, v135
	v_mul_f32_e64 v178, |v115|, s86
	v_fmac_f32_e32 v222, v77, v122
	v_fmac_f32_e32 v223, v77, v156
	v_mul_f32_e64 v179, |v117|, s86
	v_pk_mul_f32 v[220:221], v[220:221], v[172:173]
	v_fmac_f32_e32 v222, v78, v118
	v_fmac_f32_e32 v223, v78, v158
	v_exp_f32_e32 v178, v178
	v_fmac_f32_e32 v222, v79, v124
	v_fmac_f32_e32 v223, v79, v160
	v_exp_f32_e32 v179, v179
	ds_read_b128 v[76:79], v203 offset:63472
	s_waitcnt lgkmcnt(2)
	v_fmac_f32_e32 v222, v80, v121
	v_fmac_f32_e32 v223, v80, v155
	v_max_f32_e64 v115, -v115, 0
	v_fmac_f32_e32 v222, v81, v123
	v_fmac_f32_e32 v223, v81, v157
	v_max_f32_e64 v117, -v117, 0
	v_fmac_f32_e32 v222, v82, v119
	v_fmac_f32_e32 v223, v82, v159
	v_add_f32_e32 v178, 1.0, v178
	v_fmac_f32_e32 v222, v83, v125
	v_fmac_f32_e32 v223, v83, v161
	v_add_f32_e32 v179, 1.0, v179
	s_waitcnt lgkmcnt(1)
	v_fmac_f32_e32 v222, v216, v126
	v_fmac_f32_e32 v223, v216, v146
	v_log_f32_e32 v178, v178
	v_fmac_f32_e32 v222, v217, v128
	v_fmac_f32_e32 v223, v217, v148
	v_log_f32_e32 v179, v179
	v_fmac_f32_e32 v222, v218, v130
	v_fmac_f32_e32 v223, v218, v150
	v_fmac_f32_e32 v115, 0x3f317217, v178
	v_fmac_f32_e32 v222, v219, v132
	v_fmac_f32_e32 v223, v219, v152
	v_fmac_f32_e32 v117, 0x3f317217, v179
	s_waitcnt lgkmcnt(0)
	v_fmac_f32_e32 v222, v76, v127
	v_fmac_f32_e32 v223, v76, v147
	v_mul_f32_e32 v115, 0xbdb8aa3b, v115
	v_fmac_f32_e32 v222, v77, v129
	v_fmac_f32_e32 v223, v77, v149
	v_mul_f32_e32 v117, 0xbdb8aa3b, v117
	v_fmac_f32_e32 v222, v78, v131
	v_fmac_f32_e32 v223, v78, v151
	v_exp_f32_e32 v174, v115
	v_fmac_f32_e32 v222, v79, v133
	v_fmac_f32_e32 v223, v79, v153
	v_exp_f32_e32 v175, v117
	v_mul_f32_e64 v224, |v222|, s86
	v_mul_f32_e64 v225, |v223|, s86
	v_exp_f32_e32 v224, v224
	v_exp_f32_e32 v225, v225
	v_pk_mul_f32 v[220:221], v[220:221], v[174:175]
	v_max_f32_e64 v222, -v222, 0
	v_max_f32_e64 v223, -v223, 0
	v_add_f32_e32 v224, 1.0, v224
	v_add_f32_e32 v225, 1.0, v225
	v_log_f32_e32 v224, v224
	v_log_f32_e32 v225, v225
	s_nop 0
	v_fmac_f32_e32 v222, 0x3f317217, v224
	v_fmac_f32_e32 v223, 0x3f317217, v225
	v_mul_f32_e32 v222, 0xbdb8aa3b, v222
	v_mul_f32_e32 v223, 0xbdb8aa3b, v223
	v_exp_f32_e32 v176, v222
	v_exp_f32_e32 v177, v223
	s_nop 1
	v_pk_mul_f32 v[220:221], v[220:221], v[176:177]
	s_nop 0
	ds_write_b64 v192, v[220:221]
	s_waitcnt lgkmcnt(0)
	s_barrier
	ds_read2st64_b64 v[80:83], v191 offset1:1
	ds_read2st64_b64 v[76:79], v191 offset0:2 offset1:3
	s_waitcnt lgkmcnt(1)
	v_pk_mul_f32 v[178:179], v[80:81], v[82:83]
	s_waitcnt lgkmcnt(0)
	v_pk_mul_f32 v[178:179], v[178:179], v[76:77]
	s_nop 0
	v_pk_mul_f32 v[178:179], v[178:179], v[78:79]
	s_and_saveexec_b64 s[48:49], s[4:5]
	ds_write_b64 v197, v[178:179]
	s_or_b64 exec, exec, s[48:49]
	v_cndmask_b32_e64 v81, v81, 1.0, s[4:5]
	v_cndmask_b32_e64 v80, v80, 1.0, s[4:5]
	v_mul_f32_e32 v82, v80, v82
	v_mul_f32_e32 v83, v81, v83
	v_cndmask_b32_e64 v81, v81, v83, s[6:7]
	v_cndmask_b32_e64 v80, v80, v82, s[6:7]
	v_pk_mul_f32 v[76:77], v[80:81], v[76:77]
	v_add_u32_e32 v115, 0x4400, v200
	v_cndmask_b32_e64 v77, v81, v77, s[8:9]
	v_cndmask_b32_e64 v76, v80, v76, s[8:9]
	v_pk_mul_f32 v[78:79], v[76:77], v[78:79]
	v_cndmask_b32_e64 v77, v77, v79, s[10:11]
	v_cndmask_b32_e64 v76, v76, v78, s[10:11]
	v_add_u32_e32 v216, 0x0, v200
	v_add_u32_e32 v217, 0x4400, v200
	v_add_u32_e32 v117, 0x440, v200
	v_add_u32_e32 v115, 0x4840, v200
	ds_read2_b32 v[222:223], v216 offset1:68
	ds_read2_b32 v[226:227], v217 offset1:68
	ds_read2_b32 v[224:225], v216 offset0:136 offset1:204
	ds_read2_b32 v[228:229], v217 offset0:136 offset1:204
	ds_read2_b32 v[230:231], v117 offset1:68
	ds_read2_b32 v[234:235], v115 offset1:68
	ds_read2_b32 v[232:233], v117 offset0:136 offset1:204
	ds_read2_b32 v[236:237], v115 offset0:136 offset1:204
	s_waitcnt lgkmcnt(4)
	v_pk_mul_f32 v[76:77], v[76:77], v[84:85]
	v_lshlrev_b32_e32 v80, 16, v222
	v_and_b32_e32 v81, 0xffff0000, v222
	v_rcp_f32_e32 v78, v76
	v_rcp_f32_e32 v79, v77
	v_lshlrev_b32_e32 v82, 16, v226
	v_and_b32_e32 v83, 0xffff0000, v226
	v_pk_mul_f32 v[80:81], v[80:81], v[76:77]
	v_pk_mul_f32 v[220:221], v[178:179], v[78:79]
	v_pk_mul_f32 v[76:77], v[76:77], v[86:87]
	v_pk_mul_f32 v[218:219], v[82:83], v[78:79]
	v_pk_mul_f32 v[220:221], v[82:83], v[220:221]
	v_cvt_pk_bf16_f32 v222, v80, v81
	v_cvt_pk_bf16_f32 v226, v218, v219
	v_lshlrev_b32_e32 v80, 16, v223
	v_and_b32_e32 v81, 0xffff0000, v223
	v_rcp_f32_e32 v78, v76
	v_rcp_f32_e32 v79, v77
	v_lshlrev_b32_e32 v82, 16, v227
	v_and_b32_e32 v83, 0xffff0000, v227
	v_pk_mul_f32 v[80:81], v[80:81], v[76:77]
	v_pk_mul_f32 v[238:239], v[178:179], v[78:79]
	v_pk_mul_f32 v[218:219], v[82:83], v[78:79]
	v_pk_mul_f32 v[238:239], v[82:83], v[238:239]
	v_cvt_pk_bf16_f32 v223, v80, v81
	v_cvt_pk_bf16_f32 v227, v218, v219
	v_cvt_pk_bf16_f32 v80, v220, v238
	v_cvt_pk_bf16_f32 v81, v221, v239
	ds_write2_b32 v216, v222, v223 offset1:68
	ds_write2_b32 v217, v226, v227 offset1:68
	ds_write_b32 v193, v80 offset:34816
	ds_write_b32 v193, v81 offset:34960
	v_pk_mul_f32 v[76:77], v[76:77], v[88:89]
	v_lshlrev_b32_e32 v80, 16, v224
	v_and_b32_e32 v81, 0xffff0000, v224
	v_rcp_f32_e32 v78, v76
	v_rcp_f32_e32 v79, v77
	v_lshlrev_b32_e32 v82, 16, v228
	v_and_b32_e32 v83, 0xffff0000, v228
	v_pk_mul_f32 v[80:81], v[80:81], v[76:77]
	v_pk_mul_f32 v[220:221], v[178:179], v[78:79]
	v_pk_mul_f32 v[76:77], v[76:77], v[90:91]
	v_pk_mul_f32 v[218:219], v[82:83], v[78:79]
	v_pk_mul_f32 v[220:221], v[82:83], v[220:221]
	v_cvt_pk_bf16_f32 v224, v80, v81
	v_cvt_pk_bf16_f32 v228, v218, v219
	v_lshlrev_b32_e32 v80, 16, v225
	v_and_b32_e32 v81, 0xffff0000, v225
	v_rcp_f32_e32 v78, v76
	v_rcp_f32_e32 v79, v77
	v_lshlrev_b32_e32 v82, 16, v229
	v_and_b32_e32 v83, 0xffff0000, v229
	v_pk_mul_f32 v[80:81], v[80:81], v[76:77]
	v_pk_mul_f32 v[238:239], v[178:179], v[78:79]
	v_pk_mul_f32 v[218:219], v[82:83], v[78:79]
	v_pk_mul_f32 v[238:239], v[82:83], v[238:239]
	v_cvt_pk_bf16_f32 v225, v80, v81
	v_cvt_pk_bf16_f32 v229, v218, v219
	v_cvt_pk_bf16_f32 v80, v220, v238
	v_cvt_pk_bf16_f32 v81, v221, v239
	ds_write2_b32 v216, v224, v225 offset0:136 offset1:204
	ds_write2_b32 v217, v228, v229 offset0:136 offset1:204
	ds_write_b32 v193, v80 offset:34820
	ds_write_b32 v193, v81 offset:34964
	v_add_u32_e32 v216, 0x880, v200
	v_add_u32_e32 v217, 0x4c80, v200
	ds_read2_b32 v[222:223], v216 offset1:68
	ds_read2_b32 v[226:227], v217 offset1:68
	ds_read2_b32 v[224:225], v216 offset0:136 offset1:204
	ds_read2_b32 v[228:229], v217 offset0:136 offset1:204
	s_waitcnt lgkmcnt(12)
	v_pk_mul_f32 v[76:77], v[76:77], v[92:93]
	v_lshlrev_b32_e32 v80, 16, v230
	v_and_b32_e32 v81, 0xffff0000, v230
	v_rcp_f32_e32 v78, v76
	v_rcp_f32_e32 v79, v77
	v_lshlrev_b32_e32 v82, 16, v234
	v_and_b32_e32 v83, 0xffff0000, v234
	v_pk_mul_f32 v[80:81], v[80:81], v[76:77]
	v_pk_mul_f32 v[220:221], v[178:179], v[78:79]
	v_pk_mul_f32 v[76:77], v[76:77], v[94:95]
	v_pk_mul_f32 v[218:219], v[82:83], v[78:79]
	v_pk_mul_f32 v[220:221], v[82:83], v[220:221]
	v_cvt_pk_bf16_f32 v230, v80, v81
	v_cvt_pk_bf16_f32 v234, v218, v219
	v_lshlrev_b32_e32 v80, 16, v231
	v_and_b32_e32 v81, 0xffff0000, v231
	v_rcp_f32_e32 v78, v76
	v_rcp_f32_e32 v79, v77
	v_lshlrev_b32_e32 v82, 16, v235
	v_and_b32_e32 v83, 0xffff0000, v235
	v_pk_mul_f32 v[80:81], v[80:81], v[76:77]
	v_pk_mul_f32 v[238:239], v[178:179], v[78:79]
	v_pk_mul_f32 v[218:219], v[82:83], v[78:79]
	v_pk_mul_f32 v[238:239], v[82:83], v[238:239]
	v_cvt_pk_bf16_f32 v231, v80, v81
	v_cvt_pk_bf16_f32 v235, v218, v219
	v_cvt_pk_bf16_f32 v80, v220, v238
	v_cvt_pk_bf16_f32 v81, v221, v239
	ds_write2_b32 v117, v230, v231 offset1:68
	ds_write2_b32 v115, v234, v235 offset1:68
	ds_write_b32 v193, v80 offset:34824
	ds_write_b32 v193, v81 offset:34968
	v_pk_mul_f32 v[76:77], v[76:77], v[96:97]
	v_lshlrev_b32_e32 v80, 16, v232
	v_and_b32_e32 v81, 0xffff0000, v232
	v_rcp_f32_e32 v78, v76
	v_rcp_f32_e32 v79, v77
	v_lshlrev_b32_e32 v82, 16, v236
	v_and_b32_e32 v83, 0xffff0000, v236
	v_pk_mul_f32 v[80:81], v[80:81], v[76:77]
	v_pk_mul_f32 v[220:221], v[178:179], v[78:79]
	v_pk_mul_f32 v[76:77], v[76:77], v[98:99]
	v_pk_mul_f32 v[218:219], v[82:83], v[78:79]
	v_pk_mul_f32 v[220:221], v[82:83], v[220:221]
	v_cvt_pk_bf16_f32 v232, v80, v81
	v_cvt_pk_bf16_f32 v236, v218, v219
	v_lshlrev_b32_e32 v80, 16, v233
	v_and_b32_e32 v81, 0xffff0000, v233
	v_rcp_f32_e32 v78, v76
	v_rcp_f32_e32 v79, v77
	v_lshlrev_b32_e32 v82, 16, v237
	v_and_b32_e32 v83, 0xffff0000, v237
	v_pk_mul_f32 v[80:81], v[80:81], v[76:77]
	v_pk_mul_f32 v[238:239], v[178:179], v[78:79]
	v_pk_mul_f32 v[218:219], v[82:83], v[78:79]
	v_pk_mul_f32 v[238:239], v[82:83], v[238:239]
	v_cvt_pk_bf16_f32 v233, v80, v81
	v_cvt_pk_bf16_f32 v237, v218, v219
	v_cvt_pk_bf16_f32 v80, v220, v238
	v_cvt_pk_bf16_f32 v81, v221, v239
	ds_write2_b32 v117, v232, v233 offset0:136 offset1:204
	ds_write2_b32 v115, v236, v237 offset0:136 offset1:204
	ds_write_b32 v193, v80 offset:34828
	ds_write_b32 v193, v81 offset:34972
	v_add_u32_e32 v117, 0xcc0, v200
	v_add_u32_e32 v115, 0x50c0, v200
	ds_read2_b32 v[230:231], v117 offset1:68
	ds_read2_b32 v[234:235], v115 offset1:68
	ds_read2_b32 v[232:233], v117 offset0:136 offset1:204
	ds_read2_b32 v[236:237], v115 offset0:136 offset1:204
	s_waitcnt lgkmcnt(12)
	v_pk_mul_f32 v[76:77], v[76:77], v[162:163]
	v_lshlrev_b32_e32 v80, 16, v222
	v_and_b32_e32 v81, 0xffff0000, v222
	v_rcp_f32_e32 v78, v76
	v_rcp_f32_e32 v79, v77
	v_lshlrev_b32_e32 v82, 16, v226
	v_and_b32_e32 v83, 0xffff0000, v226
	v_pk_mul_f32 v[80:81], v[80:81], v[76:77]
	v_pk_mul_f32 v[220:221], v[178:179], v[78:79]
	v_pk_mul_f32 v[76:77], v[76:77], v[164:165]
	v_pk_mul_f32 v[218:219], v[82:83], v[78:79]
	v_pk_mul_f32 v[220:221], v[82:83], v[220:221]
	v_cvt_pk_bf16_f32 v222, v80, v81
	v_cvt_pk_bf16_f32 v226, v218, v219
	v_lshlrev_b32_e32 v80, 16, v223
	v_and_b32_e32 v81, 0xffff0000, v223
	v_rcp_f32_e32 v78, v76
	v_rcp_f32_e32 v79, v77
	v_lshlrev_b32_e32 v82, 16, v227
	v_and_b32_e32 v83, 0xffff0000, v227
	v_pk_mul_f32 v[80:81], v[80:81], v[76:77]
	v_pk_mul_f32 v[238:239], v[178:179], v[78:79]
	v_pk_mul_f32 v[218:219], v[82:83], v[78:79]
	v_pk_mul_f32 v[238:239], v[82:83], v[238:239]
	v_cvt_pk_bf16_f32 v223, v80, v81
	v_cvt_pk_bf16_f32 v227, v218, v219
	v_cvt_pk_bf16_f32 v80, v220, v238
	v_cvt_pk_bf16_f32 v81, v221, v239
	ds_write2_b32 v216, v222, v223 offset1:68
	ds_write2_b32 v217, v226, v227 offset1:68
	ds_write_b32 v193, v80 offset:34832
	ds_write_b32 v193, v81 offset:34976
	v_pk_mul_f32 v[76:77], v[76:77], v[166:167]
	v_lshlrev_b32_e32 v80, 16, v224
	v_and_b32_e32 v81, 0xffff0000, v224
	v_rcp_f32_e32 v78, v76
	v_rcp_f32_e32 v79, v77
	v_lshlrev_b32_e32 v82, 16, v228
	v_and_b32_e32 v83, 0xffff0000, v228
	v_pk_mul_f32 v[80:81], v[80:81], v[76:77]
	v_pk_mul_f32 v[220:221], v[178:179], v[78:79]
	v_pk_mul_f32 v[76:77], v[76:77], v[168:169]
	v_pk_mul_f32 v[218:219], v[82:83], v[78:79]
	v_pk_mul_f32 v[220:221], v[82:83], v[220:221]
	v_cvt_pk_bf16_f32 v224, v80, v81
	v_cvt_pk_bf16_f32 v228, v218, v219
	v_lshlrev_b32_e32 v80, 16, v225
	v_and_b32_e32 v81, 0xffff0000, v225
	v_rcp_f32_e32 v78, v76
	v_rcp_f32_e32 v79, v77
	v_lshlrev_b32_e32 v82, 16, v229
	v_and_b32_e32 v83, 0xffff0000, v229
	v_pk_mul_f32 v[80:81], v[80:81], v[76:77]
	v_pk_mul_f32 v[238:239], v[178:179], v[78:79]
	v_pk_mul_f32 v[218:219], v[82:83], v[78:79]
	v_pk_mul_f32 v[238:239], v[82:83], v[238:239]
	v_cvt_pk_bf16_f32 v225, v80, v81
	v_cvt_pk_bf16_f32 v229, v218, v219
	v_cvt_pk_bf16_f32 v80, v220, v238
	v_cvt_pk_bf16_f32 v81, v221, v239
	ds_write2_b32 v216, v224, v225 offset0:136 offset1:204
	ds_write2_b32 v217, v228, v229 offset0:136 offset1:204
	ds_write_b32 v193, v80 offset:34836
	ds_write_b32 v193, v81 offset:34980
	s_waitcnt lgkmcnt(8)
	v_pk_mul_f32 v[76:77], v[76:77], v[170:171]
	v_lshlrev_b32_e32 v80, 16, v230
	v_and_b32_e32 v81, 0xffff0000, v230
	v_rcp_f32_e32 v78, v76
	v_rcp_f32_e32 v79, v77
	v_lshlrev_b32_e32 v82, 16, v234
	v_and_b32_e32 v83, 0xffff0000, v234
	v_pk_mul_f32 v[80:81], v[80:81], v[76:77]
	v_pk_mul_f32 v[220:221], v[178:179], v[78:79]
	v_pk_mul_f32 v[76:77], v[76:77], v[172:173]
	v_pk_mul_f32 v[218:219], v[82:83], v[78:79]
	v_pk_mul_f32 v[220:221], v[82:83], v[220:221]
	v_cvt_pk_bf16_f32 v230, v80, v81
	v_cvt_pk_bf16_f32 v234, v218, v219
	v_lshlrev_b32_e32 v80, 16, v231
	v_and_b32_e32 v81, 0xffff0000, v231
	v_rcp_f32_e32 v78, v76
	v_rcp_f32_e32 v79, v77
	v_lshlrev_b32_e32 v82, 16, v235
	v_and_b32_e32 v83, 0xffff0000, v235
	v_pk_mul_f32 v[80:81], v[80:81], v[76:77]
	v_pk_mul_f32 v[238:239], v[178:179], v[78:79]
	v_pk_mul_f32 v[218:219], v[82:83], v[78:79]
	v_pk_mul_f32 v[238:239], v[82:83], v[238:239]
	v_cvt_pk_bf16_f32 v231, v80, v81
	v_cvt_pk_bf16_f32 v235, v218, v219
	v_cvt_pk_bf16_f32 v80, v220, v238
	v_cvt_pk_bf16_f32 v81, v221, v239
	ds_write2_b32 v117, v230, v231 offset1:68
	ds_write2_b32 v115, v234, v235 offset1:68
	ds_write_b32 v193, v80 offset:34840
	ds_write_b32 v193, v81 offset:34984
	v_pk_mul_f32 v[76:77], v[76:77], v[174:175]
	v_lshlrev_b32_e32 v80, 16, v232
	v_and_b32_e32 v81, 0xffff0000, v232
	v_rcp_f32_e32 v78, v76
	v_rcp_f32_e32 v79, v77
	v_lshlrev_b32_e32 v82, 16, v236
	v_and_b32_e32 v83, 0xffff0000, v236
	v_pk_mul_f32 v[80:81], v[80:81], v[76:77]
	v_pk_mul_f32 v[220:221], v[178:179], v[78:79]
	v_pk_mul_f32 v[76:77], v[76:77], v[176:177]
	v_pk_mul_f32 v[218:219], v[82:83], v[78:79]
	v_pk_mul_f32 v[220:221], v[82:83], v[220:221]
	v_cvt_pk_bf16_f32 v232, v80, v81
	v_cvt_pk_bf16_f32 v236, v218, v219
	v_lshlrev_b32_e32 v80, 16, v233
	v_and_b32_e32 v81, 0xffff0000, v233
	v_rcp_f32_e32 v78, v76
	v_rcp_f32_e32 v79, v77
	v_lshlrev_b32_e32 v82, 16, v237
	v_and_b32_e32 v83, 0xffff0000, v237
	v_pk_mul_f32 v[80:81], v[80:81], v[76:77]
	v_pk_mul_f32 v[238:239], v[178:179], v[78:79]
	v_pk_mul_f32 v[218:219], v[82:83], v[78:79]
	v_pk_mul_f32 v[238:239], v[82:83], v[238:239]
	v_cvt_pk_bf16_f32 v233, v80, v81
	v_cvt_pk_bf16_f32 v237, v218, v219
	v_cvt_pk_bf16_f32 v80, v220, v238
	v_cvt_pk_bf16_f32 v81, v221, v239
	ds_write2_b32 v117, v232, v233 offset0:136 offset1:204
	ds_write2_b32 v115, v236, v237 offset0:136 offset1:204
	ds_write_b32 v193, v80 offset:34844
	ds_write_b32 v193, v81 offset:34988
	s_cmp_lt_u32 s93, 4
	s_cselect_b64 s[48:49], -1, 0
	s_and_b64 vcc, exec, s[48:49]
	s_waitcnt lgkmcnt(0)
	s_barrier
	s_cbranch_vccnz .LBB0_3095
	ds_read_b128 v[76:79], v198
	v_add_u32_e32 v115, v196, v201
	ds_read_b128 v[80:83], v115 offset:17408
	ds_read_b128 v[84:87], v198 offset:64
	ds_read_b128 v[88:91], v115 offset:17472
	ds_read_b128 v[92:95], v115 offset:21760
	ds_read_b128 v[96:99], v115 offset:21824
	ds_read_b128 v[162:165], v115 offset:26112
	ds_read_b128 v[166:169], v115 offset:26176
	ds_read_b128 v[170:173], v115 offset:30464
	ds_read_b128 v[174:177], v115 offset:30528
	s_waitcnt lgkmcnt(8)
	v_mfma_f32_16x16x32_bf16 v[80:83], v[76:79], v[80:83], 0
	s_waitcnt lgkmcnt(5)
	v_mfma_f32_16x16x32_bf16 v[92:95], v[76:79], v[92:95], 0
	s_waitcnt lgkmcnt(3)
	v_mfma_f32_16x16x32_bf16 v[162:165], v[76:79], v[162:165], 0
	s_waitcnt lgkmcnt(1)
	v_mfma_f32_16x16x32_bf16 v[76:79], v[76:79], v[170:173], 0
	ds_read_b128 v[170:173], v198 offset:128
	ds_read_b128 v[216:219], v115 offset:17536
	v_mfma_f32_16x16x32_bf16 v[80:83], v[84:87], v[88:91], v[80:83]
	ds_read_b128 v[88:91], v198 offset:192
	ds_read_b128 v[220:223], v115 offset:17600
	s_waitcnt lgkmcnt(2)
	v_mfma_f32_16x16x32_bf16 v[80:83], v[170:173], v[216:219], v[80:83]
	ds_read_b128 v[216:219], v115 offset:21888
	ds_read_b128 v[224:227], v115 offset:21952
	ds_read_b128 v[228:231], v115 offset:26240
	ds_read_b128 v[232:235], v115 offset:26304
	s_waitcnt lgkmcnt(4)
	v_mfma_f32_16x16x32_bf16 v[80:83], v[88:91], v[220:223], v[80:83]
	ds_read_b128 v[220:223], v115 offset:30592
	ds_read_b128 v[236:239], v115 offset:30656
	v_mfma_f32_16x16x32_bf16 v[92:95], v[84:87], v[96:99], v[92:95]
	s_nop 4
	v_cvt_pk_bf16_f32 v80, v80, s0
	v_cndmask_b32_e64 v80, v80, 0, s[12:13]
	ds_write_b16 v204, v80 offset:62464
	v_cvt_pk_bf16_f32 v80, v81, s0
	v_cndmask_b32_e64 v80, v80, 0, s[14:15]
	s_waitcnt lgkmcnt(6)
	v_mfma_f32_16x16x32_bf16 v[92:95], v[170:173], v[216:219], v[92:95]
	ds_write_b16 v204, v80 offset:62608
	v_cvt_pk_bf16_f32 v80, v82, s0
	v_cndmask_b32_e64 v80, v80, 0, s[16:17]
	ds_write_b16 v204, v80 offset:62752
	v_cvt_pk_bf16_f32 v80, v83, s0
	v_cndmask_b32_e64 v115, v80, 0, s[18:19]
	s_waitcnt lgkmcnt(7)
	v_mfma_f32_16x16x32_bf16 v[80:83], v[88:91], v[224:227], v[92:95]
	ds_write_b16 v204, v115 offset:62896
	v_mfma_f32_16x16x32_bf16 v[96:99], v[84:87], v[166:169], v[162:165]
	v_mfma_f32_16x16x32_bf16 v[76:79], v[84:87], v[174:177], v[76:79]
	s_nop 4
	v_cvt_pk_bf16_f32 v80, v80, s0
	v_cndmask_b32_e64 v80, v80, 0, s[20:21]
	ds_write_b16 v204, v80 offset:62496
	v_cvt_pk_bf16_f32 v80, v81, s0
	v_cndmask_b32_e64 v80, v80, 0, s[22:23]
	s_waitcnt lgkmcnt(8)
	v_mfma_f32_16x16x32_bf16 v[84:87], v[170:173], v[228:231], v[96:99]
	ds_write_b16 v204, v80 offset:62640
	v_cvt_pk_bf16_f32 v80, v82, s0
	v_cndmask_b32_e64 v80, v80, 0, s[24:25]
	s_waitcnt lgkmcnt(7)
	v_mfma_f32_16x16x32_bf16 v[76:79], v[170:173], v[220:223], v[76:79]
	ds_write_b16 v204, v80 offset:62784
	v_cvt_pk_bf16_f32 v80, v83, s0
	v_cndmask_b32_e64 v92, v80, 0, s[26:27]
	v_mfma_f32_16x16x32_bf16 v[80:83], v[88:91], v[232:235], v[84:87]
	ds_write_b16 v204, v92 offset:62928
	s_waitcnt lgkmcnt(8)
	v_mfma_f32_16x16x32_bf16 v[76:79], v[88:91], v[236:239], v[76:79]
	s_nop 4
	v_cvt_pk_bf16_f32 v80, v80, s0
	s_nop 1
	v_cvt_pk_bf16_f32 v76, v76, s0
	v_cndmask_b32_e64 v80, v80, 0, s[28:29]
	v_cndmask_b32_e64 v76, v76, 0, s[38:39]
	ds_write_b16 v204, v80 offset:62528
	v_cvt_pk_bf16_f32 v80, v81, s0
	ds_write_b16 v204, v76 offset:62560
	v_cvt_pk_bf16_f32 v76, v77, s0
	v_cndmask_b32_e64 v80, v80, 0, s[30:31]
	v_cndmask_b32_e64 v76, v76, 0, s[40:41]
	ds_write_b16 v204, v80 offset:62672
	v_cvt_pk_bf16_f32 v80, v82, s0
	ds_write_b16 v204, v76 offset:62704
	v_cvt_pk_bf16_f32 v76, v78, s0
	v_cndmask_b32_e64 v80, v80, 0, s[34:35]
	v_cndmask_b32_e64 v76, v76, 0, s[42:43]
	ds_write_b16 v204, v80 offset:62816
	v_cvt_pk_bf16_f32 v80, v83, s0
	ds_write_b16 v204, v76 offset:62848
	v_cvt_pk_bf16_f32 v76, v79, s0
	v_cndmask_b32_e64 v80, v80, 0, s[36:37]
	v_cndmask_b32_e64 v76, v76, 0, s[44:45]
	ds_write_b16 v204, v80 offset:62960
	ds_write_b16 v204, v76 offset:62992
